# attention phases (SWA and FoX): one static s_setprio 1 for waves 4-7 at phase entry, reset at phase end
# speedup vs baseline: 1.0011x; 1.0011x over previous
; #define LAS __attribute__((address_space(3)))
; __device__ __forceinline__ int opaque_tid() { int t = threadIdx.x; asm volatile("" : "+v"(t)); return t; }
; __device__ __forceinline__ void stage_rows(int tid, int& rowA, int& rowB) { if (tid < 256) { rowA = tid >> 3; rowB = rowA + 32; } else { rowA = 2 * ((tid - 256) >> 3); rowB = rowA + 1; } }
; template <int VAR>
; __device__ __forceinline__ void fox_attn_phase(const bf16* QKV, const float* CUM, const float* KPART, bf16* AO, int* JST, unsigned* Q, LAS unsigned char* lds, int vcu, int G) {
;     const int tid = opaque_tid();
;     const int lane = tid & 63, wave = __builtin_amdgcn_readfirstlane(tid >> 6), r32 = lane & 31, hi = lane >> 5;
;     int rowA, rowB; stage_rows(tid, rowA, rowB);
;     volatile LAS unsigned* flags = (volatile LAS unsigned*)(lds + 2 * ABUF);
;     constexpr int NUNIT = BATCH * NH * (SEQ / 256);
;     volatile LAS int* uq = (volatile LAS int*)(lds + 2 * ABUF + 64);
;     if (tid == 0) uq[0] = (int)__hip_atomic_fetch_add(Q, 1u, __ATOMIC_RELAXED, __HIP_MEMORY_SCOPE_AGENT);
;     __syncthreads();
;     int ui = uq[0];
;     while (ui < NUNIT) {
;         int unext = 0;
;         if (tid == 0) unext = (int)__hip_atomic_fetch_add(Q, 1u, __ATOMIC_RELAXED, __HIP_MEMORY_SCOPE_AGENT);
; __global__ void __launch_bounds__(NWAVES * 64, 2) mega_fwd(Args a) {
;     ...
;         } else if (st == 2) {
;             if (!fox) swa_attn_phase((const bf16*)(ws + WS_QKV), ka->swa_sinks + j * NH, (bf16*)(ws + WS_AO), lds, vcu, G);
;             else { fox_attn_phase<0>((const bf16*)(ws + WS_QKV), (const float*)(ws + WS_CUM), (const float*)(ws + WS_KPART), (bf16*)(ws + WS_AO), (int*)(ws + WS_KPART + 65536), (unsigned*)(ws + WS_CTL) + 4096 + 64 * j, lds, vcu, G);
.LBB0_168:
	s_cmp_gt_i32 s24, 0
	s_mov_b64 s[8:9], -1
	s_cbranch_scc0 .LBB0_304
	s_waitcnt lgkmcnt(0)
	s_add_u32 s52, s64, 0x400000
	s_addc_u32 s53, s65, 0
	s_add_u32 s8, s64, 0x600000
	v_writelane_b32 v255, s70, 0
	s_addc_u32 s9, s65, 0
	s_lshl_b32 s54, s56, 5
	v_writelane_b32 v255, s71, 1
	s_mov_b32 s55, s85
	s_cmp_gt_i32 s24, 1
	s_mov_b64 s[12:13], -1
	s_cbranch_scc0 .LBB0_281
	v_readfirstlane_b32 s16, v147
	s_cmpk_lt_u32 s16, 0x100
	s_cbranch_scc1 .Lattn_prio_skip
	s_setprio 1
.Lattn_prio_skip:
	s_add_u32 s12, s64, 0x1ba00000
	s_addc_u32 s13, s65, 0
	s_add_u32 s14, s64, 0x27a00000
	s_addc_u32 s15, s65, 0
	s_mov_b64 s[16:17], -1
	s_and_b64 vcc, exec, s[18:19]
	s_cbranch_vccz .LBB0_251
	v_mov_b32_e32 v127, v147
	s_movk_i32 s16, 0x100
	s_nop 0
	v_cmp_gt_i32_e64 s[44:45], s16, v127
	s_movk_i32 s16, 0xff
	v_readfirstlane_b32 s24, v127
	v_cmp_lt_i32_e64 s[40:41], s16, v127
	v_add_u32_e32 v129, 0xffffff00, v127
	s_and_saveexec_b64 s[16:17], s[40:41]
	s_xor_b64 s[16:17], exec, s[16:17]
	v_lshrrev_b32_e32 v0, 2, v129
	v_and_b32_e32 v122, 0x3ffffffe, v0
	v_or_b32_e32 v124, 1, v0
	s_andn2_saveexec_b64 s[16:17], s[16:17]
	v_ashrrev_i32_e32 v122, 3, v127
	v_add_u32_e32 v124, 32, v122
	s_or_b64 exec, exec, s[16:17]
	s_lshl_b32 s84, s56, 6
	s_lshl_b64 s[16:17], s[84:85], 2
	s_add_u32 s16, s64, s16
	s_addc_u32 s17, s65, s17
	s_add_u32 s16, s16, 0x4000
	s_addc_u32 s17, s17, 0
	v_cmp_eq_u32_e64 s[42:43], 0, v127
	s_and_saveexec_b64 s[18:19], s[42:43]
	s_cbranch_execz .LBB0_179
	s_mov_b64 s[22:23], exec
	v_mbcnt_lo_u32_b32 v0, s22, 0
	v_mbcnt_hi_u32_b32 v0, s23, v0
	v_cmp_eq_u32_e32 vcc, 0, v0
	s_and_saveexec_b64 s[20:21], vcc
	s_cbranch_execz .LBB0_178
	s_bcnt1_i32_b64 s22, s[22:23]
	s_waitcnt vmcnt(0)
	v_mov_b32_e32 v2, s22
	global_atomic_add v2, v1, v2, s[16:17] sc0

; __global__ void __launch_bounds__(NWAVES * 64, 2) mega_fwd(Args a) {
;     ...
;         if (st == 0 || st == 3 || st == 5 || st == 6) {
;             size_t aoff, boff, ooff; int N, K, mode, ldc, ntm = 1 << 30;
;             if (st == 0) { aoff = WS_XN; ooff = WS_QKV; K = DM; mode = 0;
;                 if (!fox) { boff = WS_WSI + (size_t)j * N_SWA_IN * DM * 2; N = N_SWA_IN; ldc = N_SWA_IN; }
;                 else { boff = WS_WFI + (size_t)j * N_FOX_PAD * DM * 2; N = N_FOX_PAD; ldc = N_FOX_MAIN; ntm = N_FOX_MAIN / 256; } }
;             else if (st == 3) { aoff = WS_AO; boff = (fox ? WS_WFO : WS_WSO) + (size_t)j * DM * DM * 2; ooff = WS_Y; N = DM; K = DM; mode = 1; ldc = DM; }
;             else if (st == 5) { aoff = WS_XN; boff = WS_WGU + (size_t)layer * N_GU * DM * 2; ooff = WS_HB; N = N_GU; K = DM; mode = 2; ldc = DFF; }
;             else { aoff = WS_HB; boff = WS_WDN + (size_t)layer * DM * DFF * 2; ooff = WS_Y; N = DM; K = DFF; mode = 1; ldc = DM; }
;             pg8::Gemm gm{(const bf16*)(ws + aoff), (const bf16*)(ws + boff), M, N, K}; pg8::StaticOrder S; S.init(M, N, G, bx);
;             pg8::EpiAny E{mode, true, ws + ooff, ldc, ntm, (float*)(ws + ((st == 0 && !fox) ? WS_ROPE : WS_GATE))};
;             pg8::gemm_phase<pg8::EpiAny, pg8::StaticOrder, PG8_ALIGN, PG8_SP2>(lds, gm, S, E);
.LBB0_422:
	s_setprio 0
	s_and_b32 s4, s33, 15
	s_cmp_lg_u32 s4, 8
	s_cbranch_scc1 .Lgate_skip
	v_readfirstlane_b32 s4, v147
	v_and_b32_e32 v130, 63, v147
	s_lshr_b32 s4, s4, 6
	s_lshl_b32 s5, s4, 9
	s_lshr_b32 s6, s33, 4
	s_mul_i32 s6, s6, 0x1900000
	s_add_u32 s6, s6, 0x4800000
	s_add_u32 s6, s6, s5
	s_add_u32 s8, s60, s6
	s_addc_u32 s9, s61, 0
	v_and_b32_e32 v131, 15, v130
	v_lshrrev_b32_e32 v132, 4, v130
	v_lshlrev_b32_e32 v133, 12, v131
	v_lshl_add_u32 v134, v132, 4, v133
	v_add_u32_e32 v135, 0x10000, v134
	v_add_u32_e32 v136, 0x20000, v134
	v_add_u32_e32 v137, 0x30000, v134
	v_lshlrev_b32_e32 v138, 4, v130
	s_lshl_b32 s7, s4, 13
	v_add_u32_e32 v139, s7, v138
	s_lshl_b32 s7, s4, 10
	v_add_u32_e32 v140, s7, v138
	v_lshlrev_b32_e32 v141, 7, v131
	v_lshl_add_u32 v141, v132, 4, v141
	s_mov_b32 s12, s2
